# merge and wout phases: blocks 0-255 (two tiles each) run at s_setprio 1, reset at the end of the phase
# baseline (speedup 1.0000x reference)
.LBB0_901:
	v_readlane_b32 s98, v248, 0
	s_cmpk_lt_u32 s98, 0x100
	s_cbranch_scc0 .Lprio_mw_0
	s_setprio 1

.LBB0_908:
	s_setprio 0
	s_cmp_lt_i32 s53, 8
	s_cbranch_scc1 .LBB0_976
	s_cmp_eq_u32 s54, 0
	s_cbranch_scc1 .LBB0_921
	v_lshrrev_b32_e32 v2, 20, v0
	v_lshrrev_b32_e32 v3, 10, v0
	v_or_b32_e32 v2, v3, v2
	s_movk_i32 s0, 0x3ff
	v_and_or_b32 v2, v2, s0, v1
	v_cmp_eq_u32_e32 vcc, 0, v2
	s_waitcnt vmcnt(63) expcnt(7) lgkmcnt(15)
	s_barrier
	s_and_saveexec_b64 s[0:1], vcc
	s_cbranch_execz .LBB0_920
	v_readlane_b32 s2, v248, 2
	v_readlane_b32 s3, v248, 3
	buffer_wbl2 sc1
	s_waitcnt vmcnt(0)
	s_load_dwordx2 s[2:3], s[2:3], 0x58
	v_mov_b32_e32 v4, 0
	s_mov_b64 s[4:5], exec
	v_mbcnt_lo_u32_b32 v3, s4, 0
	v_mbcnt_hi_u32_b32 v3, s5, v3
	s_waitcnt lgkmcnt(0)
	global_load_dword v2, v4, s[2:3] offset:40
	v_cmp_eq_u32_e32 vcc, 0, v3
	s_and_saveexec_b64 s[6:7], vcc
	s_cbranch_execz .LBB0_913
	s_bcnt1_i32_b64 s4, s[4:5]
	v_mov_b32_e32 v5, s4
	global_atomic_add v5, v4, v5, s[2:3] offset:32 sc0

.LBB0_980:
	s_setprio 0
	s_cmp_lt_i32 s53, 9
	s_cbranch_scc1 .LBB0_1048
	s_cmp_eq_u32 s54, 0
	s_cbranch_scc1 .LBB0_993
	v_lshrrev_b32_e32 v2, 20, v0
	v_lshrrev_b32_e32 v3, 10, v0
	v_or_b32_e32 v2, v3, v2
	s_movk_i32 s0, 0x3ff
	v_and_or_b32 v2, v2, s0, v1
	v_cmp_eq_u32_e32 vcc, 0, v2
	s_waitcnt vmcnt(63) expcnt(7) lgkmcnt(15)
	s_barrier
	s_and_saveexec_b64 s[0:1], vcc
	s_cbranch_execz .LBB0_992
	v_readlane_b32 s2, v248, 2
	v_readlane_b32 s3, v248, 3
	buffer_wbl2 sc1
	s_waitcnt vmcnt(0)
	s_load_dwordx2 s[2:3], s[2:3], 0x58
	v_mov_b32_e32 v4, 0
	s_mov_b64 s[4:5], exec
	v_mbcnt_lo_u32_b32 v3, s4, 0
	v_mbcnt_hi_u32_b32 v3, s5, v3
	s_waitcnt lgkmcnt(0)
	global_load_dword v2, v4, s[2:3] offset:40
	v_cmp_eq_u32_e32 vcc, 0, v3
	s_and_saveexec_b64 s[6:7], vcc
	s_cbranch_execz .LBB0_985
	s_bcnt1_i32_b64 s4, s[4:5]
	v_mov_b32_e32 v5, s4
	global_atomic_add v5, v4, v5, s[2:3] offset:32 sc0

.LBB0_1800:
	s_setprio 0
	s_cmp_lt_i32 s53, 15
	s_cbranch_scc1 .LBB0_1868
	s_cmp_eq_u32 s54, 0
	s_cbranch_scc1 .LBB0_1813
	v_lshrrev_b32_e32 v2, 20, v0
	v_lshrrev_b32_e32 v3, 10, v0
	v_or_b32_e32 v2, v3, v2
	s_movk_i32 s0, 0x3ff
	v_and_or_b32 v2, v2, s0, v1
	v_cmp_eq_u32_e32 vcc, 0, v2
	s_waitcnt vmcnt(63) expcnt(7) lgkmcnt(15)
	s_barrier
	s_and_saveexec_b64 s[0:1], vcc
	s_cbranch_execz .LBB0_1812
	v_readlane_b32 s2, v248, 2
	v_readlane_b32 s3, v248, 3
	buffer_wbl2 sc1
	s_waitcnt vmcnt(0)
	s_load_dwordx2 s[2:3], s[2:3], 0x58
	v_mov_b32_e32 v4, 0
	s_mov_b64 s[4:5], exec
	v_mbcnt_lo_u32_b32 v3, s4, 0
	v_mbcnt_hi_u32_b32 v3, s5, v3
	s_waitcnt lgkmcnt(0)
	global_load_dword v2, v4, s[2:3] offset:40
	v_cmp_eq_u32_e32 vcc, 0, v3
	s_and_saveexec_b64 s[6:7], vcc
	s_cbranch_execz .LBB0_1805
	s_bcnt1_i32_b64 s4, s[4:5]
	v_mov_b32_e32 v5, s4
	global_atomic_add v5, v4, v5, s[2:3] offset:32 sc0

.LBB0_1872:
	s_setprio 0
	s_cmp_lt_i32 s53, 16
	s_cbranch_scc1 .LBB0_1940
	s_cmp_eq_u32 s54, 0
	s_cbranch_scc1 .LBB0_1885
	v_lshrrev_b32_e32 v2, 20, v0
	v_lshrrev_b32_e32 v3, 10, v0
	v_or_b32_e32 v2, v3, v2
	s_movk_i32 s0, 0x3ff
	v_and_or_b32 v2, v2, s0, v1
	v_cmp_eq_u32_e32 vcc, 0, v2
	s_waitcnt vmcnt(63) expcnt(7) lgkmcnt(15)
	s_barrier
	s_and_saveexec_b64 s[0:1], vcc
	s_cbranch_execz .LBB0_1884
	v_readlane_b32 s2, v248, 2
	v_readlane_b32 s3, v248, 3
	buffer_wbl2 sc1
	s_waitcnt vmcnt(0)
	s_load_dwordx2 s[2:3], s[2:3], 0x58
	v_mov_b32_e32 v4, 0
	s_mov_b64 s[4:5], exec
	v_mbcnt_lo_u32_b32 v3, s4, 0
	v_mbcnt_hi_u32_b32 v3, s5, v3
	s_waitcnt lgkmcnt(0)
	global_load_dword v2, v4, s[2:3] offset:40
	v_cmp_eq_u32_e32 vcc, 0, v3
	s_and_saveexec_b64 s[6:7], vcc
	s_cbranch_execz .LBB0_1877
	s_bcnt1_i32_b64 s4, s[4:5]
	v_mov_b32_e32 v5, s4
	global_atomic_add v5, v4, v5, s[2:3] offset:32 sc0
